# w_down weight transposes deferred from phase0b to the workgroups idle during the compress GEMM
# speedup vs baseline: 1.0011x; 1.0011x over previous
.LBB0_67:
	s_cmpk_gt_i32 s61, 0x68f
	s_mov_b64 s[6:7], -1
	s_cbranch_scc0 .LBB0_89
	s_cmpk_gt_u32 s61, 0x88f
	s_cbranch_scc0 .LBB0_86
	s_cmpk_gt_u32 s61, 0x138f
	s_cbranch_scc0 .LBB0_79
	s_cmpk_gt_u32 s61, 0x190f
	s_cbranch_scc1 .Lp0b_c1path
	s_cmpk_lg_i32 s76, 0x100
	s_cbranch_scc1 .LBB0_76
	s_branch .LBB0_66
.Lp0b_c1path:
	s_waitcnt lgkmcnt(0)
	v_mov_b32_e32 v16, s20
	ds_read_b64 v[16:17], v16
	s_cmpk_gt_u32 s61, 0x1a0f
	s_cbranch_scc0 .LBB0_73
	s_and_b32 s6, s14, 0xe0
	s_waitcnt lgkmcnt(0)
	v_readfirstlane_b32 s7, v16
	s_and_b32 s2, s16, 0x7c0
	s_lshl_b32 s10, s6, 2
	v_readfirstlane_b32 s11, v17
	s_add_u32 s10, s7, s10
	s_addc_u32 s11, s11, 0
	v_or_b32_e32 v34, s2, v18
	v_lshl_add_u64 v[32:33], s[10:11], 0, v[2:3]
	v_lshl_add_u64 v[32:33], v[32:33], 0, s[4:5]
	v_lshlrev_b32_e32 v34, 10, v34
	v_mov_b32_e32 v35, v3
	v_lshl_add_u64 v[36:37], v[32:33], 0, v[34:35]
	v_add_co_u32_e32 v40, vcc, s21, v36
	v_or_b32_e32 v38, 0x1000, v34
	s_nop 0
	v_addc_co_u32_e32 v41, vcc, 0, v37, vcc
	v_add_co_u32_e32 v44, vcc, s24, v36
	v_mov_b32_e32 v39, v3
	s_nop 0
	v_addc_co_u32_e32 v45, vcc, 0, v37, vcc
	v_add_co_u32_e32 v48, vcc, s25, v36
	v_or_b32_e32 v42, 0x2000, v34
	v_mov_b32_e32 v43, v3
	v_or_b32_e32 v46, 0x3000, v34
	v_mov_b32_e32 v47, v3
	v_addc_co_u32_e32 v49, vcc, 0, v37, vcc
	v_lshl_add_u64 v[38:39], v[32:33], 0, v[38:39]
	v_lshl_add_u64 v[42:43], v[32:33], 0, v[42:43]
	v_lshl_add_u64 v[46:47], v[32:33], 0, v[46:47]
	global_load_dword v54, v[36:37], off
	global_load_dword v55, v[36:37], off offset:2048
	global_load_dword v56, v[38:39], off
	global_load_dword v57, v[40:41], off offset:2048
	global_load_dword v58, v[42:43], off
	global_load_dword v59, v[44:45], off offset:2048
	global_load_dword v60, v[46:47], off
	global_load_dword v61, v[48:49], off offset:2048
	v_add_co_u32_e32 v40, vcc, s26, v36
	v_or_b32_e32 v38, 0x4000, v34
	s_nop 0
	v_addc_co_u32_e32 v41, vcc, 0, v37, vcc
	v_add_co_u32_e32 v44, vcc, s27, v36
	v_mov_b32_e32 v39, v3
	s_nop 0
	v_addc_co_u32_e32 v45, vcc, 0, v37, vcc
	v_add_co_u32_e32 v48, vcc, s28, v36
	v_lshl_add_u64 v[38:39], v[32:33], 0, v[38:39]
	s_nop 0
	v_addc_co_u32_e32 v49, vcc, 0, v37, vcc
	v_add_co_u32_e32 v52, vcc, s29, v36
	v_or_b32_e32 v42, 0x5000, v34
	v_mov_b32_e32 v43, v3
	v_or_b32_e32 v46, 0x6000, v34
	v_mov_b32_e32 v47, v3
	v_or_b32_e32 v50, 0x7000, v34
	v_mov_b32_e32 v51, v3
	v_addc_co_u32_e32 v53, vcc, 0, v37, vcc
	v_lshl_add_u64 v[42:43], v[32:33], 0, v[42:43]
	v_lshl_add_u64 v[46:47], v[32:33], 0, v[46:47]
	v_lshl_add_u64 v[50:51], v[32:33], 0, v[50:51]
	global_load_dword v62, v[38:39], off
	global_load_dword v63, v[40:41], off offset:2048
	global_load_dword v64, v[42:43], off
	global_load_dword v65, v[44:45], off offset:2048
	global_load_dword v66, v[46:47], off
	global_load_dword v67, v[48:49], off offset:2048
	global_load_dword v68, v[50:51], off
	global_load_dword v69, v[52:53], off offset:2048
	v_add_co_u32_e32 v40, vcc, s30, v36
	v_or_b32_e32 v38, 0x8000, v34
	s_nop 0
	v_addc_co_u32_e32 v41, vcc, 0, v37, vcc
	v_add_co_u32_e32 v44, vcc, s31, v36
	v_mov_b32_e32 v39, v3
	s_nop 0
	v_addc_co_u32_e32 v45, vcc, 0, v37, vcc
	v_add_co_u32_e32 v48, vcc, s33, v36
	v_or_b32_e32 v50, 0xb000, v34
	s_nop 0
	v_addc_co_u32_e32 v49, vcc, 0, v37, vcc
	v_mov_b32_e32 v51, v3
	v_add_co_u32_e32 v52, vcc, s34, v36
	v_lshl_add_u64 v[38:39], v[32:33], 0, v[38:39]
	v_or_b32_e32 v42, 0x9000, v34
	v_mov_b32_e32 v43, v3
	v_or_b32_e32 v46, 0xa000, v34
	v_mov_b32_e32 v47, v3
	v_lshl_add_u64 v[50:51], v[32:33], 0, v[50:51]
	v_addc_co_u32_e32 v53, vcc, 0, v37, vcc
	v_lshl_add_u64 v[42:43], v[32:33], 0, v[42:43]
	v_lshl_add_u64 v[46:47], v[32:33], 0, v[46:47]
	global_load_dword v70, v[38:39], off
	global_load_dword v71, v[40:41], off offset:2048
	global_load_dword v72, v[42:43], off
	global_load_dword v73, v[44:45], off offset:2048
	global_load_dword v74, v[46:47], off
	global_load_dword v75, v[48:49], off offset:2048
	s_nop 0
	global_load_dword v50, v[50:51], off
	s_nop 0
	global_load_dword v51, v[52:53], off offset:2048
	v_add_co_u32_e32 v40, vcc, s35, v36
	v_or_b32_e32 v38, 0xc000, v34
	s_nop 0
	v_addc_co_u32_e32 v41, vcc, 0, v37, vcc
	v_add_co_u32_e32 v44, vcc, s36, v36
	v_mov_b32_e32 v39, v3
	s_nop 0
	v_addc_co_u32_e32 v45, vcc, 0, v37, vcc
	v_add_co_u32_e32 v48, vcc, s37, v36
	v_or_b32_e32 v42, 0xd000, v34
	v_mov_b32_e32 v43, v3
	v_or_b32_e32 v46, 0xe000, v34
	v_mov_b32_e32 v47, v3
	v_addc_co_u32_e32 v49, vcc, 0, v37, vcc
	v_or_b32_e32 v34, 0xf000, v34
	v_lshl_add_u64 v[38:39], v[32:33], 0, v[38:39]
	v_lshl_add_u64 v[42:43], v[32:33], 0, v[42:43]
	v_lshl_add_u64 v[46:47], v[32:33], 0, v[46:47]
	v_lshl_add_u64 v[32:33], v[32:33], 0, v[34:35]
	v_add_co_u32_e32 v34, vcc, s38, v36
	s_lshl_b32 s2, s2, 1
	s_nop 0
	v_addc_co_u32_e32 v35, vcc, 0, v37, vcc
	global_load_dword v36, v[38:39], off
	global_load_dword v37, v[40:41], off offset:2048
	s_nop 0
	global_load_dword v38, v[42:43], off
	global_load_dword v39, v[44:45], off offset:2048
	global_load_dword v40, v[46:47], off
	global_load_dword v41, v[48:49], off offset:2048
	s_nop 0
	global_load_dword v32, v[32:33], off
	s_nop 0
	global_load_dword v33, v[34:35], off offset:2048
	s_waitcnt vmcnt(0)
	ds_write2_b32 v19, v54, v55 offset1:66
	ds_write2_b32 v19, v56, v57 offset0:132 offset1:198
	ds_write2_b32 v25, v58, v59 offset0:8 offset1:74
	ds_write2_b32 v25, v60, v61 offset0:140 offset1:206
	ds_write2_b32 v26, v62, v63 offset0:16 offset1:82
	ds_write2_b32 v26, v64, v65 offset0:148 offset1:214
	ds_write2_b32 v27, v66, v67 offset0:24 offset1:90
	ds_write2_b32 v27, v68, v69 offset0:156 offset1:222
	ds_write2_b32 v28, v70, v71 offset0:32 offset1:98
	ds_write2_b32 v28, v72, v73 offset0:164 offset1:230
	ds_write2_b32 v29, v74, v75 offset0:40 offset1:106
	ds_write2_b32 v29, v50, v51 offset0:172 offset1:238
	ds_write2_b32 v30, v36, v37 offset0:48 offset1:114
	ds_write2_b32 v30, v38, v39 offset0:180 offset1:246
	ds_write2_b32 v31, v40, v41 offset0:56 offset1:122
	ds_write2_b32 v31, v32, v33 offset0:188 offset1:254
	s_waitcnt lgkmcnt(0)
	ds_read2_b32 v[36:37], v21 offset1:8
	ds_read2_b32 v[40:41], v21 offset0:33 offset1:41
	ds_read2_b32 v[42:43], v21 offset0:66 offset1:74
	ds_read2_b32 v[44:45], v21 offset0:99 offset1:107
	ds_read2_b32 v[46:47], v21 offset0:132 offset1:140
	s_waitcnt lgkmcnt(4)
	v_bfe_u32 v32, v36, 16, 1
	v_add3_u32 v32, v36, v32, s39
	s_waitcnt lgkmcnt(3)
	v_bfe_u32 v33, v40, 16, 1
	v_lshrrev_b32_e32 v32, 16, v32
	v_add3_u32 v33, v40, v33, s39
	ds_read2_b32 v[48:49], v21 offset0:165 offset1:173
	v_and_or_b32 v32, v33, s40, v32
	s_waitcnt lgkmcnt(3)
	v_bfe_u32 v33, v42, 16, 1
	v_add3_u32 v33, v42, v33, s39
	s_waitcnt lgkmcnt(2)
	v_bfe_u32 v34, v44, 16, 1
	ds_read2_b32 v[50:51], v21 offset0:198 offset1:206
	v_lshrrev_b32_e32 v33, 16, v33
	v_add3_u32 v34, v44, v34, s39
	ds_read2_b32 v[52:53], v21 offset0:231 offset1:239
	v_and_or_b32 v33, v34, s40, v33
	s_waitcnt lgkmcnt(3)
	v_bfe_u32 v34, v46, 16, 1
	v_add3_u32 v34, v46, v34, s39
	s_waitcnt lgkmcnt(2)
	v_bfe_u32 v35, v48, 16, 1
	v_lshrrev_b32_e32 v34, 16, v34
	v_add3_u32 v35, v48, v35, s39
	v_and_or_b32 v34, v35, s40, v34
	s_waitcnt lgkmcnt(1)
	v_bfe_u32 v35, v50, 16, 1
	v_add3_u32 v35, v50, v35, s39
	s_waitcnt lgkmcnt(0)
	v_bfe_u32 v36, v52, 16, 1
	v_lshrrev_b32_e32 v35, 16, v35
	v_add3_u32 v36, v52, v36, s39
	v_and_or_b32 v35, v36, s40, v35
	v_or_b32_e32 v36, s6, v20
	v_lshl_add_u64 v[38:39], v[6:7], 0, s[2:3]
	v_lshlrev_b32_e32 v54, 12, v36
	v_mov_b32_e32 v55, v3
	v_lshl_add_u64 v[54:55], v[38:39], 0, v[54:55]
	global_store_dwordx4 v[54:55], v[32:35], off
	v_bfe_u32 v36, v53, 16, 1
	v_add3_u32 v36, v53, v36, s39
	v_bfe_u32 v32, v37, 16, 1
	v_add3_u32 v32, v37, v32, s39
	v_bfe_u32 v33, v41, 16, 1
	v_lshrrev_b32_e32 v32, 16, v32
	v_add3_u32 v33, v41, v33, s39
	v_and_or_b32 v32, v33, s40, v32
	v_bfe_u32 v33, v43, 16, 1
	v_add3_u32 v33, v43, v33, s39
	v_bfe_u32 v34, v45, 16, 1
	v_lshrrev_b32_e32 v33, 16, v33
	v_add3_u32 v34, v45, v34, s39
	v_and_or_b32 v33, v34, s40, v33
	v_bfe_u32 v34, v47, 16, 1
	v_add3_u32 v34, v47, v34, s39
	v_bfe_u32 v35, v49, 16, 1
	v_lshrrev_b32_e32 v34, 16, v34
	v_add3_u32 v35, v49, v35, s39
	v_and_or_b32 v34, v35, s40, v34
	v_bfe_u32 v35, v51, 16, 1
	v_add3_u32 v35, v51, v35, s39
	v_lshrrev_b32_e32 v35, 16, v35
	v_and_or_b32 v35, v36, s40, v35
	v_or_b32_e32 v36, s6, v22
	v_lshlrev_b32_e32 v36, 12, v36
	v_mov_b32_e32 v37, v3
	ds_read2_b32 v[40:41], v21 offset0:16 offset1:24
	v_lshl_add_u64 v[36:37], v[38:39], 0, v[36:37]
	global_store_dwordx4 v[36:37], v[32:35], off
	ds_read2_b32 v[36:37], v21 offset0:49 offset1:57
	ds_read2_b32 v[42:43], v21 offset0:82 offset1:90
	ds_read2_b32 v[44:45], v21 offset0:115 offset1:123
	s_waitcnt lgkmcnt(3)
	v_bfe_u32 v32, v40, 16, 1
	v_add3_u32 v32, v40, v32, s39
	s_waitcnt lgkmcnt(2)
	v_bfe_u32 v33, v36, 16, 1
	ds_read2_b32 v[46:47], v21 offset0:148 offset1:156
	v_lshrrev_b32_e32 v32, 16, v32
	v_add3_u32 v33, v36, v33, s39
	ds_read2_b32 v[48:49], v21 offset0:181 offset1:189
	v_and_or_b32 v32, v33, s40, v32
	s_waitcnt lgkmcnt(3)
	v_bfe_u32 v33, v42, 16, 1
	v_add3_u32 v33, v42, v33, s39
	s_waitcnt lgkmcnt(2)
	v_bfe_u32 v34, v44, 16, 1
	ds_read2_b32 v[50:51], v21 offset0:214 offset1:222
	v_lshrrev_b32_e32 v33, 16, v33
	v_add3_u32 v34, v44, v34, s39
	ds_read2_b32 v[52:53], v21 offset0:247 offset1:255
	v_and_or_b32 v33, v34, s40, v33
	s_waitcnt lgkmcnt(3)
	v_bfe_u32 v34, v46, 16, 1
	v_add3_u32 v34, v46, v34, s39
	s_waitcnt lgkmcnt(2)
	v_bfe_u32 v35, v48, 16, 1
	v_lshrrev_b32_e32 v34, 16, v34
	v_add3_u32 v35, v48, v35, s39
	v_and_or_b32 v34, v35, s40, v34
	s_waitcnt lgkmcnt(1)
	v_bfe_u32 v35, v50, 16, 1
	v_add3_u32 v35, v50, v35, s39
	s_waitcnt lgkmcnt(0)
	v_bfe_u32 v36, v52, 16, 1
	v_lshrrev_b32_e32 v35, 16, v35
	v_add3_u32 v36, v52, v36, s39
	v_and_or_b32 v35, v36, s40, v35
	v_or_b32_e32 v36, s6, v23
	v_lshlrev_b32_e32 v54, 12, v36
	v_mov_b32_e32 v55, v3
	v_lshl_add_u64 v[54:55], v[38:39], 0, v[54:55]
	global_store_dwordx4 v[54:55], v[32:35], off
	v_bfe_u32 v36, v53, 16, 1
	v_add3_u32 v36, v53, v36, s39
	v_bfe_u32 v32, v41, 16, 1
	v_add3_u32 v32, v41, v32, s39
	v_bfe_u32 v33, v37, 16, 1
	v_lshrrev_b32_e32 v32, 16, v32
	v_add3_u32 v33, v37, v33, s39
	v_and_or_b32 v32, v33, s40, v32
	v_bfe_u32 v33, v43, 16, 1
	v_add3_u32 v33, v43, v33, s39
	v_bfe_u32 v34, v45, 16, 1
	v_lshrrev_b32_e32 v33, 16, v33
	v_add3_u32 v34, v45, v34, s39
	v_and_or_b32 v33, v34, s40, v33
	v_bfe_u32 v34, v47, 16, 1
	v_add3_u32 v34, v47, v34, s39
	v_bfe_u32 v35, v49, 16, 1
	v_lshrrev_b32_e32 v34, 16, v34
	v_add3_u32 v35, v49, v35, s39
	v_and_or_b32 v34, v35, s40, v34
	v_bfe_u32 v35, v51, 16, 1
	v_add3_u32 v35, v51, v35, s39
	v_lshrrev_b32_e32 v35, 16, v35
	v_and_or_b32 v35, v36, s40, v35
	v_add_lshl_u32 v36, s6, v24, 12
	v_mov_b32_e32 v37, v3
	v_lshl_add_u64 v[36:37], v[38:39], 0, v[36:37]
	global_store_dwordx4 v[36:37], v[32:35], off
	s_waitcnt lgkmcnt(0)
	s_mov_b64 s[6:7], 0

.LBB0_370:
	v_readlane_b32 s68, v247, 17
	v_readlane_b32 s72, v247, 21
	v_readlane_b32 s69, v247, 18
	v_readlane_b32 s67, v247, 19
	v_readlane_b32 s71, v247, 20
	v_readlane_b32 s73, v247, 22
	s_barrier
	s_branch .LBB0_371
.Ltail2_p0b:
	s_cmpk_lg_i32 s76, 0x100
	s_cbranch_scc1 .LBB0_371
	v_writelane_b32 v248, s20, 0
	v_writelane_b32 v248, s24, 1
	v_writelane_b32 v248, s25, 2
	v_writelane_b32 v248, s26, 3
	v_writelane_b32 v248, s27, 4
	v_writelane_b32 v248, s42, 5
	v_writelane_b32 v248, s44, 6
	v_writelane_b32 v248, s46, 7
	v_writelane_b32 v248, s47, 8
	v_writelane_b32 v248, s48, 9
	v_writelane_b32 v248, s49, 10
	v_writelane_b32 v248, s50, 11
	v_writelane_b32 v248, s54, 12
	v_writelane_b32 v248, s55, 13
	v_writelane_b32 v248, s56, 14
	s_add_i32 s2, 0, 0x23fa8
	v_mov_b32_e32 v0, s2
	ds_read_b64 v[2:3], v0
	v_mbcnt_lo_u32_b32 v0, -1, 0
	v_mbcnt_hi_u32_b32 v1, -1, v0
	s_waitcnt lgkmcnt(0)
	v_readfirstlane_b32 s0, v2
	v_readfirstlane_b32 s1, v3
	s_mov_b32 s3, 0
	v_readlane_b32 s61, v247, 1
	s_add_i32 s2, s80, 0xffffff80
	s_lshl_b32 s2, s2, 3
	s_lshr_b32 s61, s61, 6
	s_add_i32 s61, s61, s2
	s_addk_i32 s61, 0x1390
	s_cmpk_gt_i32 s61, 0x190f
	s_cbranch_scc1 .Ltail2_done
	s_lshl_b32 s2, s79, 14
	v_and_b32_e32 v0, 31, v1
	v_lshrrev_b32_e32 v18, 5, v1
	s_add_i32 s2, s2, 0
	v_lshlrev_b32_e32 v2, 2, v0
	v_mul_u32_u24_e32 v4, 0x84, v18
	v_add3_u32 v19, s2, v2, v4
	v_lshlrev_b32_e32 v2, 3, v1
	v_and_b32_e32 v2, 56, v2
	v_mov_b32_e32 v3, 0
	v_mul_u32_u24_e32 v8, 0x84, v2
	v_lshlrev_b32_e32 v2, 1, v2
	v_lshrrev_b32_e32 v20, 3, v1
	v_lshl_add_u64 v[4:5], s[0:1], 0, v[2:3]
	s_mov_b64 s[4:5], 0x1b00000
	v_lshl_add_u64 v[6:7], v[4:5], 0, s[4:5]
	v_lshlrev_b32_e32 v2, 2, v20
	s_mov_b64 s[4:5], 0x1a00000
	v_add3_u32 v21, s2, v8, v2
	v_lshl_add_u64 v[8:9], v[4:5], 0, s[4:5]
	s_mov_b64 s[4:5], 0x1400000
	v_lshl_add_u64 v[10:11], v[4:5], 0, s[4:5]
	s_mov_b64 s[4:5], 0x900000
	s_lshl_b32 s2, s61, 3
	v_lshl_add_u64 v[12:13], v[4:5], 0, s[4:5]
	s_mov_b64 s[4:5], 0x700000
	s_add_i32 s16, s2, 0x780
	s_lshl_b32 s2, s61, 1
	v_add_u32_e32 v22, 8, v20
	v_or_b32_e32 v23, 16, v20
	v_add_u32_e32 v24, 24, v20
	v_lshl_add_u64 v[14:15], v[4:5], 0, s[4:5]
	s_lshl_b32 s14, s61, 5
	s_mov_b32 s15, 0x8000
	s_movk_i32 s17, 0x2000
	s_add_i32 s18, s2, 0xffffd8e0
	s_movk_i32 s19, 0x800
	s_add_i32 s20, 0, 0x23f60
	s_mov_b64 s[4:5], 0x200000
	s_movk_i32 s21, 0x1000
	s_movk_i32 s24, 0x2000
	s_movk_i32 s25, 0x3000
	s_movk_i32 s26, 0x4000
	s_movk_i32 s27, 0x5000
	s_movk_i32 s28, 0x6000
	s_movk_i32 s29, 0x7000
	s_mov_b32 s30, 0x8000
	s_mov_b32 s31, 0x9000
	s_mov_b32 s33, 0xa000
	s_mov_b32 s34, 0xb000
	s_mov_b32 s35, 0xc000
	s_mov_b32 s36, 0xd000
	s_mov_b32 s37, 0xe000
	s_mov_b32 s38, 0xf000
	s_movk_i32 s39, 0x7fff
	s_mov_b32 s40, 0xffff0000
	s_add_i32 s41, 0, 0x23f98
	s_mov_b32 s42, 0x12000
	s_mov_b32 s43, 0x16000
	s_mov_b32 s44, 0x1a000
	s_mov_b32 s45, 0x1e000
	s_mov_b32 s46, 0x22000
	s_mov_b32 s47, 0x26000
	s_mov_b32 s48, 0x2a000
	s_mov_b32 s49, 0x2e000
	s_mov_b32 s50, 0x32000
	s_mov_b32 s51, 0x36000
	s_mov_b32 s52, 0x3a000
	s_mov_b32 s53, 0x3e000
	s_movk_i32 s54, 0x1600
	s_add_i32 s55, 0, 0x23f80
	s_movk_i32 s56, 0x5800
	s_add_i32 s57, 0, 0x23f70
	s_add_i32 s58, 0, 0x23f30
	s_movk_i32 s59, 0xd18
	s_movk_i32 s60, 0x3460
	v_lshlrev_b32_e32 v2, 2, v0
	v_add_u32_e32 v25, 0x400, v19
	v_add_u32_e32 v26, 0x800, v19
	v_add_u32_e32 v27, 0xc00, v19
	v_add_u32_e32 v28, 0x1000, v19
	v_add_u32_e32 v29, 0x1400, v19
	v_add_u32_e32 v30, 0x1800, v19
	v_add_u32_e32 v31, 0x1c00, v19
	s_branch .LBB0_67_u

.LBB0_66_u:
	s_addk_i32 s61, 0x400
	s_add_i32 s14, s14, s15
	s_add_i32 s16, s16, s17
	s_add_i32 s18, s18, s19
	s_cmpk_gt_i32 s61, 0x190f
	s_cbranch_scc1 .Ltail2_done

.LBB0_152_u:
	s_or_b64 exec, exec, s[12:13]
	s_and_saveexec_b64 s[12:13], vcc
	s_cbranch_execz .LBB0_65_u
	v_add_u32_e32 v32, 62, v32
	v_mad_i64_i32 v[16:17], s[62:63], v32, s60, v[16:17]
	global_load_dword v63, v[16:17], off
	s_branch .LBB0_65_u
	s_nop 0
	s_nop 0
	s_nop 0
	s_nop 0
	s_nop 0
	s_nop 0
	s_nop 0
	s_nop 0
	s_nop 0
	s_nop 0
	s_nop 0
	s_nop 0
	s_nop 0
	s_nop 0
	s_nop 0
	s_nop 0
	s_nop 0
	s_nop 0
	s_nop 0
	s_nop 0
.Ltail2_done:
	s_mov_b64 exec, -1
	v_readlane_b32 s20, v248, 0
	v_readlane_b32 s24, v248, 1
	v_readlane_b32 s25, v248, 2
	v_readlane_b32 s26, v248, 3
	v_readlane_b32 s27, v248, 4
	v_readlane_b32 s42, v248, 5
	v_readlane_b32 s44, v248, 6
	v_readlane_b32 s46, v248, 7
	v_readlane_b32 s47, v248, 8
	v_readlane_b32 s48, v248, 9
	v_readlane_b32 s49, v248, 10
	v_readlane_b32 s50, v248, 11
	v_readlane_b32 s54, v248, 12
	v_readlane_b32 s55, v248, 13
	v_readlane_b32 s56, v248, 14
	s_nop 3

	.amdhsa_kernel _Z14fwd_megakernel4Args
		.amdhsa_group_segment_fixed_size 16384
		.amdhsa_private_segment_fixed_size 0
		.amdhsa_kernarg_size 432
		.amdhsa_user_sgpr_count 2
		.amdhsa_user_sgpr_dispatch_ptr 0
		.amdhsa_user_sgpr_queue_ptr 0
		.amdhsa_user_sgpr_kernarg_segment_ptr 1
		.amdhsa_user_sgpr_dispatch_id 0
		.amdhsa_user_sgpr_kernarg_preload_length 0
		.amdhsa_user_sgpr_kernarg_preload_offset 0
		.amdhsa_user_sgpr_private_segment_size 0
		.amdhsa_uses_dynamic_stack 0
		.amdhsa_enable_private_segment 0
		.amdhsa_system_sgpr_workgroup_id_x 1
		.amdhsa_system_sgpr_workgroup_id_y 0
		.amdhsa_system_sgpr_workgroup_id_z 0
		.amdhsa_system_sgpr_workgroup_info 0
		.amdhsa_system_vgpr_workitem_id 2
		.amdhsa_next_free_vgpr 256
		.amdhsa_next_free_sgpr 102
		.amdhsa_accum_offset 256
		.amdhsa_reserve_vcc 1
		.amdhsa_float_round_mode_32 0
		.amdhsa_float_round_mode_16_64 0
		.amdhsa_float_denorm_mode_32 3
		.amdhsa_float_denorm_mode_16_64 3
		.amdhsa_dx10_clamp 1
		.amdhsa_ieee_mode 1
		.amdhsa_fp16_overflow 0
		.amdhsa_tg_split 0
		.amdhsa_exception_fp_ieee_invalid_op 0
		.amdhsa_exception_fp_denorm_src 0
		.amdhsa_exception_fp_ieee_div_zero 0
		.amdhsa_exception_fp_ieee_overflow 0
		.amdhsa_exception_fp_ieee_underflow 0
		.amdhsa_exception_fp_ieee_inexact 0
		.amdhsa_exception_int_div_zero 0
	.end_amdhsa_kernel

amdhsa.kernels:
  - .agpr_count:     0
    .args:
      - .offset:         0
        .size:           176
        .value_kind:     by_value
      - .offset:         176
        .size:           4
        .value_kind:     hidden_block_count_x
      - .offset:         180
        .size:           4
        .value_kind:     hidden_block_count_y
      - .offset:         184
        .size:           4
        .value_kind:     hidden_block_count_z
      - .offset:         188
        .size:           2
        .value_kind:     hidden_group_size_x
      - .offset:         190
        .size:           2
        .value_kind:     hidden_group_size_y
      - .offset:         192
        .size:           2
        .value_kind:     hidden_group_size_z
      - .offset:         194
        .size:           2
        .value_kind:     hidden_remainder_x
      - .offset:         196
        .size:           2
        .value_kind:     hidden_remainder_y
      - .offset:         198
        .size:           2
        .value_kind:     hidden_remainder_z
      - .offset:         216
        .size:           8
        .value_kind:     hidden_global_offset_x
      - .offset:         224
        .size:           8
        .value_kind:     hidden_global_offset_y
      - .offset:         232
        .size:           8
        .value_kind:     hidden_global_offset_z
      - .offset:         240
        .size:           2
        .value_kind:     hidden_grid_dims
      - .offset:         264
        .size:           8
        .value_kind:     hidden_multigrid_sync_arg
      - .offset:         296
        .size:           4
        .value_kind:     hidden_dynamic_lds_size
    .group_segment_fixed_size: 16384
    .kernarg_segment_align: 8
    .kernarg_segment_size: 432
    .language:       OpenCL C
    .language_version:
      - 2
      - 0
    .max_flat_workgroup_size: 512
    .name:           _Z14fwd_megakernel4Args
    .private_segment_fixed_size: 0
    .sgpr_count:     108
    .sgpr_spill_count: 120
    .symbol:         _Z14fwd_megakernel4Args.kd
    .uniform_work_group_size: 1
    .uses_dynamic_stack: false
    .vgpr_count:     256
    .vgpr_spill_count: 0
    .wavefront_size: 64
